# dilated unit: V staged row-major (6 ds_write_b128 per thread instead of 48 transposing ds_write_b16) and read with ds_read_b64_tr_b16
# baseline (speedup 1.0000x reference)
; #define LAS __attribute__((address_space(3)))
; DI void attn_dil_unit(LAS unsigned char* lds, const AttnArgs a) {
;     ...
; #pragma unroll
;         for (int i = 0; i < 6; ++i) {
;             const int c = tid + 512 * i, row = c >> 3, ch = c & 7;
;             *(LAS u32x4*)(Kl + row * KLD + ch * 8) = kr[i];
;             const u32x4 v = vr[i];
;             LAS bf16_t* dst = Vl + (ch * 8) * VLD + (row ^ (ch << 2));
;             dst[0 * VLD] = (bf16_t)(v.x & 0xffff); dst[1 * VLD] = (bf16_t)(v.x >> 16);
;             dst[2 * VLD] = (bf16_t)(v.y & 0xffff); dst[3 * VLD] = (bf16_t)(v.y >> 16);
;             dst[4 * VLD] = (bf16_t)(v.z & 0xffff); dst[5 * VLD] = (bf16_t)(v.z >> 16);
;             dst[6 * VLD] = (bf16_t)(v.w & 0xffff); dst[7 * VLD] = (bf16_t)(v.w >> 16);
;         }
;     }
;     __syncthreads();
;     ...
;             const LAS bf16_t* vp = Vl + (d * 32 + r32) * VLD + 32 * wid + 32 * j;
;             const int sw = (((d * 32 + r32) >> 3) & 7) << 2;
.LBB0_232:
	s_or_b64 exec, exec, s[6:7]
	v_and_b32_e32 v57, 7, v96
	s_waitcnt vmcnt(0)
	v_lshl_add_u32 v56, v57, 4, v240
	s_movk_i32 s1, 0x1870
	v_mad_u32_u24 v60, v57, s1, v56
	v_lshlrev_b32_e32 v57, 2, v57
	s_movk_i32 s1, 0x90
	v_mad_u64_u32 v[58:59], s[4:5], v50, s1, v[56:57]
	ds_write_b128 v58, v[22:25]
	v_lshlrev_b32_e32 v61, 1, v50
	v_and_b32_e32 v61, 4, v61
	v_lshrrev_b32_e32 v62, 2, v57
	v_xor_b32_e32 v61, v62, v61
	v_lshlrev_b32_e32 v61, 4, v61
	v_lshl_add_u32 v61, v50, 7, v61
	v_add_u32_e32 v61, 0xd900, v61
	v_add_u32_e32 v62, 0x6000, v61
	ds_write_b128 v61, v[2:5] offset:0
	ds_write_b128 v61, v[6:9] offset:8192
	ds_write_b128 v61, v[10:13] offset:16384
	ds_write_b128 v62, v[14:17] offset:0
	ds_write_b128 v62, v[18:21] offset:8192
	ds_write_b128 v62, v[26:29] offset:16384
	v_mad_u64_u32 v[2:3], s[4:5], v51, s1, v[56:57]
	ds_write_b128 v2, v[30:33]
	v_mad_u64_u32 v[2:3], s[4:5], v52, s1, v[56:57]
	ds_write_b128 v2, v[34:37]
	v_mad_u64_u32 v[2:3], s[4:5], v53, s1, v[56:57]
	ds_write_b128 v2, v[38:41]
	v_mad_u64_u32 v[2:3], s[4:5], v54, s1, v[56:57]
	ds_write_b128 v2, v[42:45]
	v_mad_u64_u32 v[2:3], s[4:5], v55, s1, v[56:57]
	ds_write_b128 v2, v[46:49]
	v_or_b32_e32 v2, s0, v101
	v_mul_lo_u32 v2, v2, s1
	s_movk_i32 s1, 0x100
	v_add3_u32 v0, s1, v0, v2
	s_waitcnt lgkmcnt(0)
	s_barrier
	v_lshlrev_b32_e32 v183, 2, v100
	v_sub_u32_e32 v183, v101, v183
	v_add_u32_e32 v184, 0x80, v183
	v_min_u32_e32 v185, 0x80, v98
	v_sub_u32_e32 v186, v184, v185
	v_lshlrev_b32_e32 v182, 2, v183
	v_add_u32_e32 v182, 0x19c94, v182
	s_ashr_i32 s15, s14, 31
	v_readfirstlane_b32 s4, v98
	s_mov_b32 s1, 0x3e38aa3b
	v_and_b32_e32 v198, 3, v243
	v_bfe_u32 v199, v243, 2, 2
	v_bfe_u32 v192, v243, 4, 1
	v_lshrrev_b32_e32 v193, 1, v198
	v_lshl_or_b32 v193, v192, 1, v193
	v_and_b32_e32 v192, 2, v199
	v_lshl_or_b32 v193, v192, 1, v193
	v_lshlrev_b32_e32 v193, 4, v193
	v_and_b32_e32 v198, 1, v198
	v_lshl_or_b32 v193, v198, 3, v193
	v_lshl_or_b32 v193, v199, 7, v193
	v_lshl_or_b32 v193, v100, 9, v193
	s_lshl_b32 s5, s0, 7
	v_add_u32_e32 v193, s5, v193
	v_add_u32_e32 v190, 0xd900, v193
	v_xor_b32_e32 v191, 64, v190
	s_cmp_ge_u32 s4, 0x80
	s_cselect_b32 s5, 1, 0
	v_mov_b32_e32 v187, v239
	ds_read_b128 v[2:5], v0 offset:0
	ds_read_b128 v[6:9], v0 offset:32
	ds_read_b128 v[10:13], v0 offset:64
	ds_read_b128 v[14:17], v0 offset:96
	ds_read2_b32 v[34:35], v182 offset0:155 offset1:154
	ds_read2_b32 v[36:37], v182 offset0:153 offset1:152
	ds_read2_b32 v[38:39], v182 offset0:147 offset1:146
	ds_read2_b32 v[40:41], v182 offset0:145 offset1:144
	ds_read2_b32 v[42:43], v182 offset0:139 offset1:138
	ds_read2_b32 v[44:45], v182 offset0:137 offset1:136
	ds_read2_b32 v[46:47], v182 offset0:131 offset1:130
	ds_read2_b32 v[48:49], v182 offset0:129 offset1:128
	s_waitcnt lgkmcnt(0)
	v_mfma_f32_32x32x16_bf16 v[102:117], v[2:5], v[66:69], 0
	v_mfma_f32_32x32x16_bf16 v[102:117], v[6:9], v[90:93], v[102:117]
	v_mfma_f32_32x32x16_bf16 v[102:117], v[10:13], v[86:89], v[102:117]
	v_mfma_f32_32x32x16_bf16 v[102:117], v[14:17], v[82:85], v[102:117]
	ds_read_b128 v[2:5], v0 offset:4608
	ds_read_b128 v[6:9], v0 offset:4640
	ds_read_b128 v[10:13], v0 offset:4672
	ds_read_b128 v[14:17], v0 offset:4704
	ds_read2_b32 v[50:51], v182 offset0:123 offset1:122
	ds_read2_b32 v[52:53], v182 offset0:121 offset1:120
	ds_read2_b32 v[54:55], v182 offset0:115 offset1:114
	ds_read2_b32 v[56:57], v182 offset0:113 offset1:112
	ds_read2_b32 v[58:59], v182 offset0:107 offset1:106
	ds_read2_b32 v[60:61], v182 offset0:105 offset1:104
	ds_read2_b32 v[62:63], v182 offset0:99 offset1:98
	ds_read2_b32 v[64:65], v182 offset0:97 offset1:96
	s_waitcnt lgkmcnt(0)
; #define LAS __attribute__((address_space(3)))
; DI int crow(int i, int hh) { return (i & 3) + 8 * (i >> 2) + 4 * hh; }
; #define MFMA32(a, b, c) __builtin_amdgcn_mfma_f32_32x32x16_bf16((a), (b), (c), 0, 0, 0)
; DI void attn_dil_unit(LAS unsigned char* lds, const AttnArgs a) {
;     ...
;     for (int j = 0; j < 5; ++j) {
; #pragma unroll
;         for (int i = 0; i < 16; ++i) sc[j][i] = 0.f;
; #pragma unroll
;         for (int ks = 0; ks < 4; ++ks) {
;             const bf16x8 kf = *(const LAS bf16x8*)(Kl + (32 * wid + 32 * j + r32) * KLD + ks * 16 + 8 * hh);
;             sc[j] = MFMA32(kf, qf[ks], sc[j]);
;         }
;     }
;     float mx = -1e30f;
; #pragma unroll
;     for (int j = 0; j < 5; ++j)
; #pragma unroll
;         for (int i = 0; i < 16; ++i) {
;             const int st = r32 + 128 - 32 * j - crow(i, hh);
;             const int kj = qi - st;
;             const bool valid = (st >= 0) && (st <= 128) && (kj >= 0);
;             float x = sc[j][i] * a.c2 + biasL[min(max(st, 0), 128)];
;             x = valid ? x : -1e30f;
;             sc[j][i] = x; mx = fmaxf(mx, x);
;         }
	v_mfma_f32_32x32x16_bf16 v[118:133], v[2:5], v[66:69], 0
	v_mfma_f32_32x32x16_bf16 v[118:133], v[6:9], v[90:93], v[118:133]
	v_mfma_f32_32x32x16_bf16 v[118:133], v[10:13], v[86:89], v[118:133]
	v_mfma_f32_32x32x16_bf16 v[118:133], v[14:17], v[82:85], v[118:133]
	ds_read_b128 v[2:5], v0 offset:9216
	ds_read_b128 v[6:9], v0 offset:9248
	ds_read_b128 v[10:13], v0 offset:9280
	ds_read_b128 v[14:17], v0 offset:9312
	v_fma_f32 v102, v102, s1, v34
	v_fma_f32 v103, v103, s1, v35
	v_fma_f32 v104, v104, s1, v36
	v_fma_f32 v105, v105, s1, v37
	v_fma_f32 v106, v106, s1, v38
	v_fma_f32 v107, v107, s1, v39
	v_fma_f32 v108, v108, s1, v40
	v_fma_f32 v109, v109, s1, v41
	v_fma_f32 v110, v110, s1, v42
	v_fma_f32 v111, v111, s1, v43
	v_fma_f32 v112, v112, s1, v44
	v_fma_f32 v113, v113, s1, v45
	v_fma_f32 v114, v114, s1, v46
	v_fma_f32 v115, v115, s1, v47
	v_fma_f32 v116, v116, s1, v48
	v_fma_f32 v117, v117, s1, v49
	v_sub_u32_e32 v198, 0, v186
	v_sub_u32_e32 v199, 1, v186
	v_sub_u32_e32 v188, 2, v186
	v_sub_u32_e32 v189, 3, v186
	v_cmp_ge_u32_e64 s[6:7], v185, v198
	v_cmp_ge_u32_e64 s[8:9], v185, v199
	v_cmp_ge_u32_e64 s[10:11], v185, v188
	v_cmp_ge_u32_e64 s[12:13], v185, v189
	v_cndmask_b32_e64 v102, v239, v102, s[6:7]
	v_cndmask_b32_e64 v103, v239, v103, s[8:9]
	v_cndmask_b32_e64 v104, v239, v104, s[10:11]
	v_cndmask_b32_e64 v105, v239, v105, s[12:13]
	v_sub_u32_e32 v198, 8, v186
	v_sub_u32_e32 v199, 9, v186
	v_sub_u32_e32 v188, 10, v186
	v_sub_u32_e32 v189, 11, v186
	v_cmp_ge_u32_e64 s[6:7], v185, v198
	v_cmp_ge_u32_e64 s[8:9], v185, v199
	v_cmp_ge_u32_e64 s[10:11], v185, v188
	v_cmp_ge_u32_e64 s[12:13], v185, v189
	v_cndmask_b32_e64 v106, v239, v106, s[6:7]
	v_cndmask_b32_e64 v107, v239, v107, s[8:9]
	v_cndmask_b32_e64 v108, v239, v108, s[10:11]
	v_cndmask_b32_e64 v109, v239, v109, s[12:13]
	v_sub_u32_e32 v198, 16, v186
	v_sub_u32_e32 v199, 17, v186
	v_sub_u32_e32 v188, 18, v186
	v_sub_u32_e32 v189, 19, v186
	v_cmp_ge_u32_e64 s[6:7], v185, v198
	v_cmp_ge_u32_e64 s[8:9], v185, v199
	v_cmp_ge_u32_e64 s[10:11], v185, v188
	v_cmp_ge_u32_e64 s[12:13], v185, v189
	v_cndmask_b32_e64 v110, v239, v110, s[6:7]
	v_cndmask_b32_e64 v111, v239, v111, s[8:9]
	v_cndmask_b32_e64 v112, v239, v112, s[10:11]
	v_cndmask_b32_e64 v113, v239, v113, s[12:13]
	v_sub_u32_e32 v198, 24, v186
	v_sub_u32_e32 v199, 25, v186
	v_sub_u32_e32 v188, 26, v186
	v_sub_u32_e32 v189, 27, v186
	v_cmp_ge_u32_e64 s[6:7], v185, v198
	v_cmp_ge_u32_e64 s[8:9], v185, v199
	v_cmp_ge_u32_e64 s[10:11], v185, v188
	v_cmp_ge_u32_e64 s[12:13], v185, v189
	v_cndmask_b32_e64 v114, v239, v114, s[6:7]
	v_cndmask_b32_e64 v115, v239, v115, s[8:9]
	v_cndmask_b32_e64 v116, v239, v116, s[10:11]
	v_cndmask_b32_e64 v117, v239, v117, s[12:13]
	v_max3_f32 v187, v187, v102, v103
	v_max3_f32 v187, v187, v104, v105
	v_max3_f32 v187, v187, v106, v107
	v_max3_f32 v187, v187, v108, v109
	v_max3_f32 v187, v187, v110, v111
	v_max3_f32 v187, v187, v112, v113
	v_max3_f32 v187, v187, v114, v115
	v_max3_f32 v187, v187, v116, v117
	ds_read2_b32 v[34:35], v182 offset0:91 offset1:90
	ds_read2_b32 v[36:37], v182 offset0:89 offset1:88
	ds_read2_b32 v[38:39], v182 offset0:83 offset1:82
	ds_read2_b32 v[40:41], v182 offset0:81 offset1:80
	ds_read2_b32 v[42:43], v182 offset0:75 offset1:74
	ds_read2_b32 v[44:45], v182 offset0:73 offset1:72
	ds_read2_b32 v[46:47], v182 offset0:67 offset1:66
	ds_read2_b32 v[48:49], v182 offset0:65 offset1:64
	s_waitcnt lgkmcnt(0)
	v_mfma_f32_32x32x16_bf16 v[134:149], v[2:5], v[66:69], 0
	v_mfma_f32_32x32x16_bf16 v[134:149], v[6:9], v[90:93], v[134:149]
	v_mfma_f32_32x32x16_bf16 v[134:149], v[10:13], v[86:89], v[134:149]
	v_mfma_f32_32x32x16_bf16 v[134:149], v[14:17], v[82:85], v[134:149]
	ds_read_b128 v[2:5], v0 offset:13824
	ds_read_b128 v[6:9], v0 offset:13856
	ds_read_b128 v[10:13], v0 offset:13888
	ds_read_b128 v[14:17], v0 offset:13920
	v_subrev_u32_e32 v186, 32, v186
	v_fma_f32 v118, v118, s1, v50
	v_fma_f32 v119, v119, s1, v51
	v_fma_f32 v120, v120, s1, v52
	v_fma_f32 v121, v121, s1, v53
	v_fma_f32 v122, v122, s1, v54
	v_fma_f32 v123, v123, s1, v55
	v_fma_f32 v124, v124, s1, v56
	v_fma_f32 v125, v125, s1, v57
	v_fma_f32 v126, v126, s1, v58
	v_fma_f32 v127, v127, s1, v59
	v_fma_f32 v128, v128, s1, v60
	v_fma_f32 v129, v129, s1, v61
	v_fma_f32 v130, v130, s1, v62
	v_fma_f32 v131, v131, s1, v63
	v_fma_f32 v132, v132, s1, v64
	v_fma_f32 v133, v133, s1, v65
	s_cmp_lg_u32 s5, 0
	s_cbranch_scc1 .Ldil_nomask1
	v_sub_u32_e32 v198, 0, v186
	v_sub_u32_e32 v199, 1, v186
	v_sub_u32_e32 v188, 2, v186
	v_sub_u32_e32 v189, 3, v186
	v_cmp_ge_u32_e64 s[6:7], v185, v198
	v_cmp_ge_u32_e64 s[8:9], v185, v199
	v_cmp_ge_u32_e64 s[10:11], v185, v188
	v_cmp_ge_u32_e64 s[12:13], v185, v189
	v_cndmask_b32_e64 v118, v239, v118, s[6:7]
	v_cndmask_b32_e64 v119, v239, v119, s[8:9]
	v_cndmask_b32_e64 v120, v239, v120, s[10:11]
	v_cndmask_b32_e64 v121, v239, v121, s[12:13]
	v_sub_u32_e32 v198, 8, v186
	v_sub_u32_e32 v199, 9, v186
	v_sub_u32_e32 v188, 10, v186
	v_sub_u32_e32 v189, 11, v186
	v_cmp_ge_u32_e64 s[6:7], v185, v198
	v_cmp_ge_u32_e64 s[8:9], v185, v199
	v_cmp_ge_u32_e64 s[10:11], v185, v188
	v_cmp_ge_u32_e64 s[12:13], v185, v189
	v_cndmask_b32_e64 v122, v239, v122, s[6:7]
	v_cndmask_b32_e64 v123, v239, v123, s[8:9]
	v_cndmask_b32_e64 v124, v239, v124, s[10:11]
	v_cndmask_b32_e64 v125, v239, v125, s[12:13]
	v_sub_u32_e32 v198, 16, v186
	v_sub_u32_e32 v199, 17, v186
	v_sub_u32_e32 v188, 18, v186
	v_sub_u32_e32 v189, 19, v186
	v_cmp_ge_u32_e64 s[6:7], v185, v198
	v_cmp_ge_u32_e64 s[8:9], v185, v199
	v_cmp_ge_u32_e64 s[10:11], v185, v188
	v_cmp_ge_u32_e64 s[12:13], v185, v189
	v_cndmask_b32_e64 v126, v239, v126, s[6:7]
	v_cndmask_b32_e64 v127, v239, v127, s[8:9]
	v_cndmask_b32_e64 v128, v239, v128, s[10:11]
	v_cndmask_b32_e64 v129, v239, v129, s[12:13]
	v_sub_u32_e32 v198, 24, v186
	v_sub_u32_e32 v199, 25, v186
	v_sub_u32_e32 v188, 26, v186
	v_sub_u32_e32 v189, 27, v186
	v_cmp_ge_u32_e64 s[6:7], v185, v198
	v_cmp_ge_u32_e64 s[8:9], v185, v199
	v_cmp_ge_u32_e64 s[10:11], v185, v188
	v_cmp_ge_u32_e64 s[12:13], v185, v189
	v_cndmask_b32_e64 v130, v239, v130, s[6:7]
	v_cndmask_b32_e64 v131, v239, v131, s[8:9]
	v_cndmask_b32_e64 v132, v239, v132, s[10:11]
	v_cndmask_b32_e64 v133, v239, v133, s[12:13]

; #define LAS __attribute__((address_space(3)))
; DI float ex2(float x) { return __builtin_amdgcn_exp2f(x); }
; DI int crow(int i, int hh) { return (i & 3) + 8 * (i >> 2) + 4 * hh; }
; #define MFMA32(a, b, c) __builtin_amdgcn_mfma_f32_32x32x16_bf16((a), (b), (c), 0, 0, 0)
; #define VFRAG2(off) __builtin_shufflevector(*(const LAS s16x4*)(vp + (((off) + 4 * hh) ^ sw)), *(const LAS s16x4*)(vp + (((off) + 8 + 4 * hh) ^ sw)), 0, 1, 2, 3, 4, 5, 6, 7)
; DI void attn_dil_unit(LAS unsigned char* lds, const AttnArgs a) {
;     ...
;     float mx = -1e30f;
; #pragma unroll
;     for (int j = 0; j < 5; ++j)
; #pragma unroll
;         for (int i = 0; i < 16; ++i) {
;             const int st = r32 + 128 - 32 * j - crow(i, hh);
;             const int kj = qi - st;
;             const bool valid = (st >= 0) && (st <= 128) && (kj >= 0);
;             float x = sc[j][i] * a.c2 + biasL[min(max(st, 0), 128)];
;             x = valid ? x : -1e30f;
;             sc[j][i] = x; mx = fmaxf(mx, x);
;         }
;     mx = fmaxf(mx, __shfl_xor(mx, 32));
;     float ls = 0.f;
; #pragma unroll
;     for (int j = 0; j < 5; ++j)
; #pragma unroll
;         for (int i = 0; i < 16; ++i) { const float p = (sc[j][i] > -1e29f) ? ex2(sc[j][i] - mx) : 0.f; sc[j][i] = p; ls += p; }
;     const float lt = ls + __shfl_xor(ls, 32);
;     f32x16 o[2];
; #pragma unroll
;     for (int d = 0; d < 2; ++d)
; #pragma unroll
;         for (int i = 0; i < 16; ++i) o[d][i] = 0.f;
; #pragma unroll
;     for (int j = 0; j < 5; ++j) {
;         const bf16x8 pb0 = pack8(sc[j], 0), pb1 = pack8(sc[j], 1);
; #pragma unroll
;         for (int d = 0; d < 2; ++d) {
;             const LAS bf16_t* vp = Vl + (d * 32 + r32) * VLD + 32 * wid + 32 * j;
;             const int sw = (((d * 32 + r32) >> 3) & 7) << 2;
;     ...
;             o[d] = MFMA32(VFRAG2(0), pb0, o[d]);
;             o[d] = MFMA32(VFRAG2(16), pb1, o[d]);
.Ldil_nomask3:
	v_max3_f32 v187, v187, v150, v151
	v_max3_f32 v187, v187, v152, v153
	v_max3_f32 v187, v187, v154, v155
	v_max3_f32 v187, v187, v156, v157
	v_max3_f32 v187, v187, v158, v159
	v_max3_f32 v187, v187, v160, v161
	v_max3_f32 v187, v187, v162, v163
	v_max3_f32 v187, v187, v164, v165
	s_waitcnt lgkmcnt(0)
	v_subrev_u32_e32 v186, 32, v186
	v_fma_f32 v166, v166, s1, v34
	v_fma_f32 v167, v167, s1, v35
	v_fma_f32 v168, v168, s1, v36
	v_fma_f32 v169, v169, s1, v37
	v_fma_f32 v170, v170, s1, v38
	v_fma_f32 v171, v171, s1, v39
	v_fma_f32 v172, v172, s1, v40
	v_fma_f32 v173, v173, s1, v41
	v_fma_f32 v174, v174, s1, v42
	v_fma_f32 v175, v175, s1, v43
	v_fma_f32 v176, v176, s1, v44
	v_fma_f32 v177, v177, s1, v45
	v_fma_f32 v178, v178, s1, v46
	v_fma_f32 v179, v179, s1, v47
	v_fma_f32 v180, v180, s1, v48
	v_fma_f32 v181, v181, s1, v49
	v_sub_u32_e32 v198, 0, v186
	v_sub_u32_e32 v199, 1, v186
	v_sub_u32_e32 v188, 2, v186
	v_sub_u32_e32 v189, 3, v186
	v_cmp_ge_u32_e64 s[6:7], v185, v198
	v_cmp_ge_u32_e64 s[8:9], v185, v199
	v_cmp_ge_u32_e64 s[10:11], v185, v188
	v_cmp_ge_u32_e64 s[12:13], v185, v189
	v_cndmask_b32_e64 v166, v239, v166, s[6:7]
	v_cndmask_b32_e64 v167, v239, v167, s[8:9]
	v_cndmask_b32_e64 v168, v239, v168, s[10:11]
	v_cndmask_b32_e64 v169, v239, v169, s[12:13]
	v_sub_u32_e32 v198, 8, v186
	v_sub_u32_e32 v199, 9, v186
	v_sub_u32_e32 v188, 10, v186
	v_sub_u32_e32 v189, 11, v186
	v_cmp_ge_u32_e64 s[6:7], v185, v198
	v_cmp_ge_u32_e64 s[8:9], v185, v199
	v_cmp_ge_u32_e64 s[10:11], v185, v188
	v_cmp_ge_u32_e64 s[12:13], v185, v189
	v_cndmask_b32_e64 v170, v239, v170, s[6:7]
	v_cndmask_b32_e64 v171, v239, v171, s[8:9]
	v_cndmask_b32_e64 v172, v239, v172, s[10:11]
	v_cndmask_b32_e64 v173, v239, v173, s[12:13]
	v_sub_u32_e32 v198, 16, v186
	v_sub_u32_e32 v199, 17, v186
	v_sub_u32_e32 v188, 18, v186
	v_sub_u32_e32 v189, 19, v186
	v_cmp_ge_u32_e64 s[6:7], v185, v198
	v_cmp_ge_u32_e64 s[8:9], v185, v199
	v_cmp_ge_u32_e64 s[10:11], v185, v188
	v_cmp_ge_u32_e64 s[12:13], v185, v189
	v_cndmask_b32_e64 v174, v239, v174, s[6:7]
	v_cndmask_b32_e64 v175, v239, v175, s[8:9]
	v_cndmask_b32_e64 v176, v239, v176, s[10:11]
	v_cndmask_b32_e64 v177, v239, v177, s[12:13]
	v_sub_u32_e32 v198, 24, v186
	v_sub_u32_e32 v199, 25, v186
	v_sub_u32_e32 v188, 26, v186
	v_sub_u32_e32 v189, 27, v186
	v_cmp_ge_u32_e64 s[6:7], v185, v198
	v_cmp_ge_u32_e64 s[8:9], v185, v199
	v_cmp_ge_u32_e64 s[10:11], v185, v188
	v_cmp_ge_u32_e64 s[12:13], v185, v189
	v_cndmask_b32_e64 v178, v239, v178, s[6:7]
	v_cndmask_b32_e64 v179, v239, v179, s[8:9]
	v_cndmask_b32_e64 v180, v239, v180, s[10:11]
	v_cndmask_b32_e64 v181, v239, v181, s[12:13]
	v_max3_f32 v187, v187, v166, v167
	v_max3_f32 v187, v187, v168, v169
	v_max3_f32 v187, v187, v170, v171
	v_max3_f32 v187, v187, v172, v173
	v_max3_f32 v187, v187, v174, v175
	v_max3_f32 v187, v187, v176, v177
	v_max3_f32 v187, v187, v178, v179
	v_max3_f32 v187, v187, v180, v181
	v_and_b32_e32 v198, 64, v243
	v_xor_b32_e32 v199, 32, v243
	v_add_u32_e32 v198, 64, v198
	v_cmp_lt_i32_e32 vcc, v199, v198
	s_nop 1
	v_cndmask_b32_e32 v199, v243, v199, vcc
	v_lshlrev_b32_e32 v199, 2, v199
	ds_bpermute_b32 v198, v199, v187
	ds_read_b64_tr_b16 v[34:35], v190 offset:0
	ds_read_b64_tr_b16 v[36:37], v190 offset:1024
	ds_read_b64_tr_b16 v[38:39], v191 offset:0
	ds_read_b64_tr_b16 v[40:41], v191 offset:1024
	ds_read_b64_tr_b16 v[42:43], v190 offset:2048
	ds_read_b64_tr_b16 v[44:45], v190 offset:3072
	ds_read_b64_tr_b16 v[46:47], v191 offset:2048
	ds_read_b64_tr_b16 v[48:49], v191 offset:3072
	s_waitcnt lgkmcnt(8)
	v_max_f32_e32 v88, v187, v198
	v_mov_b32_e32 v188, 0
	v_mov_b32_e32 v189, 0
	v_sub_f32_e32 v102, v102, v88
	v_sub_f32_e32 v103, v103, v88
	v_sub_f32_e32 v104, v104, v88
	v_sub_f32_e32 v105, v105, v88
	v_sub_f32_e32 v106, v106, v88
	v_sub_f32_e32 v107, v107, v88
	v_sub_f32_e32 v108, v108, v88
	v_sub_f32_e32 v109, v109, v88
	v_exp_f32_e32 v102, v102
	v_exp_f32_e32 v103, v103
	v_exp_f32_e32 v104, v104
	v_exp_f32_e32 v105, v105
	v_exp_f32_e32 v106, v106
	v_exp_f32_e32 v107, v107
	v_exp_f32_e32 v108, v108
	v_exp_f32_e32 v109, v109
	v_pk_add_f32 v[188:189], v[188:189], v[102:103]
	v_pk_add_f32 v[188:189], v[188:189], v[104:105]
	v_pk_add_f32 v[188:189], v[188:189], v[106:107]
	v_pk_add_f32 v[188:189], v[188:189], v[108:109]
	v_cvt_pk_bf16_f32 v102, v102, v103
	v_cvt_pk_bf16_f32 v103, v104, v105
	v_cvt_pk_bf16_f32 v104, v106, v107
	v_cvt_pk_bf16_f32 v105, v108, v109
	s_nop 1
	s_waitcnt lgkmcnt(4)
	v_mfma_f32_32x32x16_bf16 v[18:33], v[34:37], v[102:105], 0
	v_mfma_f32_32x32x16_bf16 v[2:17], v[38:41], v[102:105], 0
	ds_read_b64_tr_b16 v[34:35], v190 offset:4096
	ds_read_b64_tr_b16 v[36:37], v190 offset:5120
	ds_read_b64_tr_b16 v[38:39], v191 offset:4096
	ds_read_b64_tr_b16 v[40:41], v191 offset:5120
	v_sub_f32_e32 v110, v110, v88
	v_sub_f32_e32 v111, v111, v88
	v_sub_f32_e32 v112, v112, v88
	v_sub_f32_e32 v113, v113, v88
	v_sub_f32_e32 v114, v114, v88
	v_sub_f32_e32 v115, v115, v88
	v_sub_f32_e32 v116, v116, v88
	v_sub_f32_e32 v117, v117, v88
	v_exp_f32_e32 v110, v110
	v_exp_f32_e32 v111, v111
	v_exp_f32_e32 v112, v112
	v_exp_f32_e32 v113, v113
	v_exp_f32_e32 v114, v114
	v_exp_f32_e32 v115, v115
	v_exp_f32_e32 v116, v116
	v_exp_f32_e32 v117, v117
	v_pk_add_f32 v[188:189], v[188:189], v[110:111]
	v_pk_add_f32 v[188:189], v[188:189], v[112:113]
	v_pk_add_f32 v[188:189], v[188:189], v[114:115]
	v_pk_add_f32 v[188:189], v[188:189], v[116:117]
	v_cvt_pk_bf16_f32 v110, v110, v111
	v_cvt_pk_bf16_f32 v111, v112, v113
	v_cvt_pk_bf16_f32 v112, v114, v115
	v_cvt_pk_bf16_f32 v113, v116, v117
	s_nop 1
	s_waitcnt lgkmcnt(4)
; #define LAS __attribute__((address_space(3)))
; #define MFMA32(a, b, c) __builtin_amdgcn_mfma_f32_32x32x16_bf16((a), (b), (c), 0, 0, 0)
; #define VFRAG2(off) __builtin_shufflevector(*(const LAS s16x4*)(vp + (((off) + 4 * hh) ^ sw)), *(const LAS s16x4*)(vp + (((off) + 8 + 4 * hh) ^ sw)), 0, 1, 2, 3, 4, 5, 6, 7)
; DI void attn_dil_unit(LAS unsigned char* lds, const AttnArgs a) {
;     ...
;     for (int j = 0; j < 5; ++j) {
;         const bf16x8 pb0 = pack8(sc[j], 0), pb1 = pack8(sc[j], 1);
; #pragma unroll
;         for (int d = 0; d < 2; ++d) {
;             const LAS bf16_t* vp = Vl + (d * 32 + r32) * VLD + 32 * wid + 32 * j;
;             const int sw = (((d * 32 + r32) >> 3) & 7) << 2;
;     ...
;             o[d] = MFMA32(VFRAG2(0), pb0, o[d]);
;             o[d] = MFMA32(VFRAG2(16), pb1, o[d]);
	v_mfma_f32_32x32x16_bf16 v[18:33], v[42:45], v[110:113], v[18:33]
	v_mfma_f32_32x32x16_bf16 v[2:17], v[46:49], v[110:113], v[2:17]
	ds_read_b64_tr_b16 v[42:43], v190 offset:6144
	ds_read_b64_tr_b16 v[44:45], v190 offset:7168
	ds_read_b64_tr_b16 v[46:47], v191 offset:6144
	ds_read_b64_tr_b16 v[48:49], v191 offset:7168
	v_sub_f32_e32 v118, v118, v88
	v_sub_f32_e32 v119, v119, v88
	v_sub_f32_e32 v120, v120, v88
	v_sub_f32_e32 v121, v121, v88
	v_sub_f32_e32 v122, v122, v88
	v_sub_f32_e32 v123, v123, v88
	v_sub_f32_e32 v124, v124, v88
	v_sub_f32_e32 v125, v125, v88
	v_exp_f32_e32 v118, v118
	v_exp_f32_e32 v119, v119
	v_exp_f32_e32 v120, v120
	v_exp_f32_e32 v121, v121
	v_exp_f32_e32 v122, v122
	v_exp_f32_e32 v123, v123
	v_exp_f32_e32 v124, v124
	v_exp_f32_e32 v125, v125
	v_pk_add_f32 v[188:189], v[188:189], v[118:119]
	v_pk_add_f32 v[188:189], v[188:189], v[120:121]
	v_pk_add_f32 v[188:189], v[188:189], v[122:123]
	v_pk_add_f32 v[188:189], v[188:189], v[124:125]
	v_cvt_pk_bf16_f32 v118, v118, v119
	v_cvt_pk_bf16_f32 v119, v120, v121
	v_cvt_pk_bf16_f32 v120, v122, v123
	v_cvt_pk_bf16_f32 v121, v124, v125
	s_nop 1
	s_waitcnt lgkmcnt(4)
	v_mfma_f32_32x32x16_bf16 v[18:33], v[34:37], v[118:121], v[18:33]
	v_mfma_f32_32x32x16_bf16 v[2:17], v[38:41], v[118:121], v[2:17]
	ds_read_b64_tr_b16 v[34:35], v190 offset:8192
	ds_read_b64_tr_b16 v[36:37], v190 offset:9216
	ds_read_b64_tr_b16 v[38:39], v191 offset:8192
	ds_read_b64_tr_b16 v[40:41], v191 offset:9216
	v_sub_f32_e32 v126, v126, v88
	v_sub_f32_e32 v127, v127, v88
	v_sub_f32_e32 v128, v128, v88
	v_sub_f32_e32 v129, v129, v88
	v_sub_f32_e32 v130, v130, v88
	v_sub_f32_e32 v131, v131, v88
	v_sub_f32_e32 v132, v132, v88
	v_sub_f32_e32 v133, v133, v88
	v_exp_f32_e32 v126, v126
	v_exp_f32_e32 v127, v127
	v_exp_f32_e32 v128, v128
	v_exp_f32_e32 v129, v129
	v_exp_f32_e32 v130, v130
	v_exp_f32_e32 v131, v131
	v_exp_f32_e32 v132, v132
	v_exp_f32_e32 v133, v133
	v_pk_add_f32 v[188:189], v[188:189], v[126:127]
	v_pk_add_f32 v[188:189], v[188:189], v[128:129]
	v_pk_add_f32 v[188:189], v[188:189], v[130:131]
	v_pk_add_f32 v[188:189], v[188:189], v[132:133]
	v_cvt_pk_bf16_f32 v126, v126, v127
	v_cvt_pk_bf16_f32 v127, v128, v129
	v_cvt_pk_bf16_f32 v128, v130, v131
	v_cvt_pk_bf16_f32 v129, v132, v133
	s_nop 1
	s_waitcnt lgkmcnt(4)
	v_mfma_f32_32x32x16_bf16 v[18:33], v[42:45], v[126:129], v[18:33]
	v_mfma_f32_32x32x16_bf16 v[2:17], v[46:49], v[126:129], v[2:17]
	ds_read_b64_tr_b16 v[42:43], v190 offset:10240
	ds_read_b64_tr_b16 v[44:45], v190 offset:11264
	ds_read_b64_tr_b16 v[46:47], v191 offset:10240
	ds_read_b64_tr_b16 v[48:49], v191 offset:11264
	v_sub_f32_e32 v134, v134, v88
	v_sub_f32_e32 v135, v135, v88
	v_sub_f32_e32 v136, v136, v88
	v_sub_f32_e32 v137, v137, v88
	v_sub_f32_e32 v138, v138, v88
	v_sub_f32_e32 v139, v139, v88
	v_sub_f32_e32 v140, v140, v88
	v_sub_f32_e32 v141, v141, v88
	v_exp_f32_e32 v134, v134
	v_exp_f32_e32 v135, v135
	v_exp_f32_e32 v136, v136
	v_exp_f32_e32 v137, v137
	v_exp_f32_e32 v138, v138
	v_exp_f32_e32 v139, v139
	v_exp_f32_e32 v140, v140
	v_exp_f32_e32 v141, v141
	v_pk_add_f32 v[188:189], v[188:189], v[134:135]
	v_pk_add_f32 v[188:189], v[188:189], v[136:137]
	v_pk_add_f32 v[188:189], v[188:189], v[138:139]
	v_pk_add_f32 v[188:189], v[188:189], v[140:141]
	v_cvt_pk_bf16_f32 v134, v134, v135
	v_cvt_pk_bf16_f32 v135, v136, v137
	v_cvt_pk_bf16_f32 v136, v138, v139
	v_cvt_pk_bf16_f32 v137, v140, v141
	s_nop 1
	s_waitcnt lgkmcnt(4)
	v_mfma_f32_32x32x16_bf16 v[18:33], v[34:37], v[134:137], v[18:33]
	v_mfma_f32_32x32x16_bf16 v[2:17], v[38:41], v[134:137], v[2:17]
	ds_read_b64_tr_b16 v[34:35], v190 offset:12288
	ds_read_b64_tr_b16 v[36:37], v190 offset:13312
	ds_read_b64_tr_b16 v[38:39], v191 offset:12288
	ds_read_b64_tr_b16 v[40:41], v191 offset:13312
	v_sub_f32_e32 v142, v142, v88
	v_sub_f32_e32 v143, v143, v88
	v_sub_f32_e32 v144, v144, v88
	v_sub_f32_e32 v145, v145, v88
	v_sub_f32_e32 v146, v146, v88
	v_sub_f32_e32 v147, v147, v88
	v_sub_f32_e32 v148, v148, v88
	v_sub_f32_e32 v149, v149, v88
	v_exp_f32_e32 v142, v142
	v_exp_f32_e32 v143, v143
	v_exp_f32_e32 v144, v144
	v_exp_f32_e32 v145, v145
	v_exp_f32_e32 v146, v146
	v_exp_f32_e32 v147, v147
	v_exp_f32_e32 v148, v148
	v_exp_f32_e32 v149, v149
	v_pk_add_f32 v[188:189], v[188:189], v[142:143]
	v_pk_add_f32 v[188:189], v[188:189], v[144:145]
	v_pk_add_f32 v[188:189], v[188:189], v[146:147]
	v_pk_add_f32 v[188:189], v[188:189], v[148:149]
	v_cvt_pk_bf16_f32 v142, v142, v143
	v_cvt_pk_bf16_f32 v143, v144, v145
	v_cvt_pk_bf16_f32 v144, v146, v147
	v_cvt_pk_bf16_f32 v145, v148, v149
	s_nop 1
	s_waitcnt lgkmcnt(4)
; #define LAS __attribute__((address_space(3)))
; DI float lg2(float x) { return __builtin_amdgcn_logf(x); }
; #define MFMA32(a, b, c) __builtin_amdgcn_mfma_f32_32x32x16_bf16((a), (b), (c), 0, 0, 0)
; #define VFRAG2(off) __builtin_shufflevector(*(const LAS s16x4*)(vp + (((off) + 4 * hh) ^ sw)), *(const LAS s16x4*)(vp + (((off) + 8 + 4 * hh) ^ sw)), 0, 1, 2, 3, 4, 5, 6, 7)
; DI void attn_dil_unit(LAS unsigned char* lds, const AttnArgs a) {
;     ...
;     for (int j = 0; j < 5; ++j) {
;         const bf16x8 pb0 = pack8(sc[j], 0), pb1 = pack8(sc[j], 1);
; #pragma unroll
;         for (int d = 0; d < 2; ++d) {
;             const LAS bf16_t* vp = Vl + (d * 32 + r32) * VLD + 32 * wid + 32 * j;
;             const int sw = (((d * 32 + r32) >> 3) & 7) << 2;
;     ...
;             o[d] = MFMA32(VFRAG2(0), pb0, o[d]);
;             o[d] = MFMA32(VFRAG2(16), pb1, o[d]);
;     ...
;         }
;     }
;     const float inv = 1.0f / lt;
;     if (hh == 0) a.lse[qtok * a.ldl] = mx + lg2(lt);
	v_mfma_f32_32x32x16_bf16 v[18:33], v[42:45], v[142:145], v[18:33]
	v_mfma_f32_32x32x16_bf16 v[2:17], v[46:49], v[142:145], v[2:17]
	ds_read_b64_tr_b16 v[42:43], v190 offset:14336
	ds_read_b64_tr_b16 v[44:45], v190 offset:15360
	ds_read_b64_tr_b16 v[46:47], v191 offset:14336
	ds_read_b64_tr_b16 v[48:49], v191 offset:15360
	v_sub_f32_e32 v150, v150, v88
	v_sub_f32_e32 v151, v151, v88
	v_sub_f32_e32 v152, v152, v88
	v_sub_f32_e32 v153, v153, v88
	v_sub_f32_e32 v154, v154, v88
	v_sub_f32_e32 v155, v155, v88
	v_sub_f32_e32 v156, v156, v88
	v_sub_f32_e32 v157, v157, v88
	v_exp_f32_e32 v150, v150
	v_exp_f32_e32 v151, v151
	v_exp_f32_e32 v152, v152
	v_exp_f32_e32 v153, v153
	v_exp_f32_e32 v154, v154
	v_exp_f32_e32 v155, v155
	v_exp_f32_e32 v156, v156
	v_exp_f32_e32 v157, v157
	v_pk_add_f32 v[188:189], v[188:189], v[150:151]
	v_pk_add_f32 v[188:189], v[188:189], v[152:153]
	v_pk_add_f32 v[188:189], v[188:189], v[154:155]
	v_pk_add_f32 v[188:189], v[188:189], v[156:157]
	v_cvt_pk_bf16_f32 v150, v150, v151
	v_cvt_pk_bf16_f32 v151, v152, v153
	v_cvt_pk_bf16_f32 v152, v154, v155
	v_cvt_pk_bf16_f32 v153, v156, v157
	s_nop 1
	s_waitcnt lgkmcnt(4)
	v_mfma_f32_32x32x16_bf16 v[18:33], v[34:37], v[150:153], v[18:33]
	v_mfma_f32_32x32x16_bf16 v[2:17], v[38:41], v[150:153], v[2:17]
	ds_read_b64_tr_b16 v[34:35], v190 offset:16384
	ds_read_b64_tr_b16 v[36:37], v190 offset:17408
	ds_read_b64_tr_b16 v[38:39], v191 offset:16384
	ds_read_b64_tr_b16 v[40:41], v191 offset:17408
	v_sub_f32_e32 v158, v158, v88
	v_sub_f32_e32 v159, v159, v88
	v_sub_f32_e32 v160, v160, v88
	v_sub_f32_e32 v161, v161, v88
	v_sub_f32_e32 v162, v162, v88
	v_sub_f32_e32 v163, v163, v88
	v_sub_f32_e32 v164, v164, v88
	v_sub_f32_e32 v165, v165, v88
	v_exp_f32_e32 v158, v158
	v_exp_f32_e32 v159, v159
	v_exp_f32_e32 v160, v160
	v_exp_f32_e32 v161, v161
	v_exp_f32_e32 v162, v162
	v_exp_f32_e32 v163, v163
	v_exp_f32_e32 v164, v164
	v_exp_f32_e32 v165, v165
	v_pk_add_f32 v[188:189], v[188:189], v[158:159]
	v_pk_add_f32 v[188:189], v[188:189], v[160:161]
	v_pk_add_f32 v[188:189], v[188:189], v[162:163]
	v_pk_add_f32 v[188:189], v[188:189], v[164:165]
	v_cvt_pk_bf16_f32 v158, v158, v159
	v_cvt_pk_bf16_f32 v159, v160, v161
	v_cvt_pk_bf16_f32 v160, v162, v163
	v_cvt_pk_bf16_f32 v161, v164, v165
	s_nop 1
	s_waitcnt lgkmcnt(4)
	v_mfma_f32_32x32x16_bf16 v[18:33], v[42:45], v[158:161], v[18:33]
	v_mfma_f32_32x32x16_bf16 v[2:17], v[46:49], v[158:161], v[2:17]
	ds_read_b64_tr_b16 v[42:43], v190 offset:18432
	ds_read_b64_tr_b16 v[44:45], v190 offset:19456
	ds_read_b64_tr_b16 v[46:47], v191 offset:18432
	ds_read_b64_tr_b16 v[48:49], v191 offset:19456
	v_sub_f32_e32 v166, v166, v88
	v_sub_f32_e32 v167, v167, v88
	v_sub_f32_e32 v168, v168, v88
	v_sub_f32_e32 v169, v169, v88
	v_sub_f32_e32 v170, v170, v88
	v_sub_f32_e32 v171, v171, v88
	v_sub_f32_e32 v172, v172, v88
	v_sub_f32_e32 v173, v173, v88
	v_exp_f32_e32 v166, v166
	v_exp_f32_e32 v167, v167
	v_exp_f32_e32 v168, v168
	v_exp_f32_e32 v169, v169
	v_exp_f32_e32 v170, v170
	v_exp_f32_e32 v171, v171
	v_exp_f32_e32 v172, v172
	v_exp_f32_e32 v173, v173
	v_pk_add_f32 v[188:189], v[188:189], v[166:167]
	v_pk_add_f32 v[188:189], v[188:189], v[168:169]
	v_pk_add_f32 v[188:189], v[188:189], v[170:171]
	v_pk_add_f32 v[188:189], v[188:189], v[172:173]
	v_cvt_pk_bf16_f32 v166, v166, v167
	v_cvt_pk_bf16_f32 v167, v168, v169
	v_cvt_pk_bf16_f32 v168, v170, v171
	v_cvt_pk_bf16_f32 v169, v172, v173
	s_nop 1
	s_waitcnt lgkmcnt(4)
	v_mfma_f32_32x32x16_bf16 v[18:33], v[34:37], v[166:169], v[18:33]
	v_mfma_f32_32x32x16_bf16 v[2:17], v[38:41], v[166:169], v[2:17]
	v_sub_f32_e32 v174, v174, v88
	v_sub_f32_e32 v175, v175, v88
	v_sub_f32_e32 v176, v176, v88
	v_sub_f32_e32 v177, v177, v88
	v_sub_f32_e32 v178, v178, v88
	v_sub_f32_e32 v179, v179, v88
	v_sub_f32_e32 v180, v180, v88
	v_sub_f32_e32 v181, v181, v88
	v_exp_f32_e32 v174, v174
	v_exp_f32_e32 v175, v175
	v_exp_f32_e32 v176, v176
	v_exp_f32_e32 v177, v177
	v_exp_f32_e32 v178, v178
	v_exp_f32_e32 v179, v179
	v_exp_f32_e32 v180, v180
	v_exp_f32_e32 v181, v181
	v_pk_add_f32 v[188:189], v[188:189], v[174:175]
	v_pk_add_f32 v[188:189], v[188:189], v[176:177]
	v_pk_add_f32 v[188:189], v[188:189], v[178:179]
	v_pk_add_f32 v[188:189], v[188:189], v[180:181]
	v_cvt_pk_bf16_f32 v174, v174, v175
	v_cvt_pk_bf16_f32 v175, v176, v177
	v_cvt_pk_bf16_f32 v176, v178, v179
	v_cvt_pk_bf16_f32 v177, v180, v181
	s_nop 1
	s_waitcnt lgkmcnt(0)
	v_mfma_f32_32x32x16_bf16 v[18:33], v[42:45], v[174:177], v[18:33]
	v_mfma_f32_32x32x16_bf16 v[2:17], v[46:49], v[174:177], v[2:17]
	v_add_f32_e32 v188, v188, v189
	ds_bpermute_b32 v0, v199, v188
	v_lshlrev_b32_e32 v92, 2, v100
	v_cmp_eq_u32_e32 vcc, 0, v100
	s_waitcnt lgkmcnt(0)
	v_add_f32_e32 v0, v188, v0
	s_and_saveexec_b64 s[6:7], vcc
	s_cbranch_execz .LBB0_227
	s_lshl_b64 s[0:1], s[14:15], 18
	v_readlane_b32 s4, v255, 9
	v_log_f32_e32 v34, v0
	v_readlane_b32 s5, v255, 10
	s_add_u32 s0, s4, s0
	s_addc_u32 s1, s5, s1
	s_lshl_b32 s4, s21, 2
	s_add_u32 s0, s0, s4
	s_addc_u32 s1, s1, 0
	v_add_f32_e32 v36, v88, v34
	v_lshlrev_b64 v[34:35], 5, v[94:95]
	v_lshl_add_u64 v[34:35], s[0:1], 0, v[34:35]
	global_store_dword v[34:35], v36, off
	s_branch .LBB0_227
